# v98 + diff near-diagonal tiles: 16 T5 table reads share one base register via ds_read2_b32 offset fields (15 v_add_u32 fewer per tile)
# speedup vs baseline: 1.0077x; 1.0077x over previous
; #define LAS __attribute__((address_space(3)))
; template <int MODE, int NDG> ...
;     ...
;     LAS const unsigned char* kp = kst + r32 * 144 + hi * 16;
;     {   f32x16 z;
; #pragma unroll
;         for (int r = 0; r < 16; ++r) z[r] = 0.f;
;         const bf16x8 a0 = lds16(kp), a1 = lds16(kp + 32 * 144);
;         p0 = __builtin_amdgcn_mfma_f32_32x32x16_bf16(a0, qr[0], MODE == MODE_SB ? z : negm, 0, 0, 0);
;         p1 = __builtin_amdgcn_mfma_f32_32x32x16_bf16(a1, qr[0], MODE == MODE_SB ? z : negm, 0, 0, 0); }
; #pragma unroll
;     for (int d0 = 1; d0 < 4; ++d0) {
;         const bf16x8 a0 = lds16(kp + d0 * 32), a1 = lds16(kp + 32 * 144 + d0 * 32);
;         p0 = __builtin_amdgcn_mfma_f32_32x32x16_bf16(a0, qr[d0], p0, 0, 0, 0);
;         p1 = __builtin_amdgcn_mfma_f32_32x32x16_bf16(a1, qr[d0], p1, 0, 0, 0);
;     }
;     ...
;     if (MODE == MODE_DIFF) {
;         if (k0 + 63 + 113 > qw0) {
;             LAS const float* rt = dtab + (207 - (qw0 - k0 + r32 - 4 * hi));
; #pragma unroll
;             for (int r = 0; r < 16; ++r) { p0[r] += rt[(r & 3) + 8 * (r >> 2)]; p1[r] += rt[(r & 3) + 8 * (r >> 2) + 32]; }
;         }
.LBB0_191:
	ds_read_b128 v[4:7], v222 offset:9216
	ds_read_b128 v[8:11], v222 offset:9248
	s_cmp_le_u32 s51, s46
	s_waitcnt lgkmcnt(1)
	v_mfma_f32_32x32x16_bf16 v[112:127], v[4:7], v[136:139], v[80:95]
	ds_read_b128 v[4:7], v222 offset:13824
	ds_read_b128 v[12:15], v222 offset:13856
	s_waitcnt lgkmcnt(1)
	v_mfma_f32_32x32x16_bf16 v[96:111], v[4:7], v[136:139], v[80:95]
	v_mfma_f32_32x32x16_bf16 v[112:127], v[8:11], v[144:147], v[112:127]
	ds_read_b128 v[4:7], v222 offset:9280
	ds_read_b128 v[8:11], v222 offset:9312
	s_waitcnt lgkmcnt(2)
	v_mfma_f32_32x32x16_bf16 v[96:111], v[12:15], v[144:147], v[96:111]
	s_waitcnt lgkmcnt(1)
	v_mfma_f32_32x32x16_bf16 v[112:127], v[4:7], v[148:151], v[112:127]
	ds_read_b128 v[4:7], v222 offset:13888
	ds_read_b128 v[12:15], v222 offset:13920
	s_waitcnt lgkmcnt(1)
	v_mfma_f32_32x32x16_bf16 v[96:111], v[4:7], v[148:151], v[96:111]
	v_mfma_f32_32x32x16_bf16 v[112:127], v[8:11], v[152:155], v[112:127]
	s_waitcnt lgkmcnt(0)
	v_mfma_f32_32x32x16_bf16 v[96:111], v[12:15], v[152:155], v[96:111]
	s_cbranch_scc1 .LBB0_193
	v_add_u32_e32 v198, s47, v221
	v_add_u32_e32 v198, 0x2243c, v198
	ds_read2_b32 v[0:1], v198 offset1:1
	ds_read2_b32 v[4:5], v198 offset0:32 offset1:33
	ds_read2_b32 v[6:7], v198 offset0:2 offset1:3
	ds_read2_b32 v[8:9], v198 offset0:34 offset1:35
	ds_read2_b32 v[10:11], v198 offset0:8 offset1:9
	ds_read2_b32 v[12:13], v198 offset0:40 offset1:41
	ds_read2_b32 v[14:15], v198 offset0:10 offset1:11
	ds_read2_b32 v[194:195], v198 offset0:42 offset1:43
	ds_read2_b32 v[202:203], v198 offset0:16 offset1:17
	ds_read2_b32 v[224:225], v198 offset0:48 offset1:49
	ds_read2_b32 v[226:227], v198 offset0:18 offset1:19
	ds_read2_b32 v[228:229], v198 offset0:50 offset1:51
	ds_read2_b32 v[230:231], v198 offset0:26 offset1:27
	ds_read2_b32 v[232:233], v198 offset0:24 offset1:25
	ds_read2_b32 v[234:235], v198 offset0:56 offset1:57
	ds_read2_b32 v[236:237], v198 offset0:58 offset1:59
	s_waitcnt lgkmcnt(5)
	v_add_f32_e32 v122, v122, v226
	v_add_f32_e32 v123, v123, v227
	s_waitcnt lgkmcnt(3)
	v_add_f32_e32 v126, v126, v230
	v_add_f32_e32 v127, v127, v231
	s_waitcnt lgkmcnt(2)
	v_add_f32_e32 v124, v124, v232
	v_add_f32_e32 v125, v125, v233
	v_add_f32_e32 v120, v120, v202
	v_add_f32_e32 v121, v121, v203
	v_add_f32_e32 v118, v118, v14
	v_add_f32_e32 v119, v119, v15
	v_add_f32_e32 v116, v116, v10
	v_add_f32_e32 v117, v117, v11
	v_add_f32_e32 v114, v114, v6
	v_add_f32_e32 v115, v115, v7
	v_add_f32_e32 v112, v112, v0
	v_add_f32_e32 v113, v113, v1
	s_waitcnt lgkmcnt(0)
	v_add_f32_e32 v110, v110, v236
	v_add_f32_e32 v111, v111, v237
	v_add_f32_e32 v108, v108, v234
	v_add_f32_e32 v109, v109, v235
	v_add_f32_e32 v106, v106, v228
	v_add_f32_e32 v107, v107, v229
	v_add_f32_e32 v104, v104, v224
	v_add_f32_e32 v105, v105, v225
	v_add_f32_e32 v102, v102, v194
	v_add_f32_e32 v103, v103, v195
	v_add_f32_e32 v100, v100, v12
	v_add_f32_e32 v101, v101, v13
	v_add_f32_e32 v98, v98, v8
	v_add_f32_e32 v99, v99, v9
	v_add_f32_e32 v96, v96, v4
	v_add_f32_e32 v97, v97, v5

; #define LAS __attribute__((address_space(3)))
; template <int MODE, int NDG> ...
;     ...
;     LAS const unsigned char* kp = kst + r32 * 144 + hi * 16;
;     {   f32x16 z;
; #pragma unroll
;         for (int r = 0; r < 16; ++r) z[r] = 0.f;
;         const bf16x8 a0 = lds16(kp), a1 = lds16(kp + 32 * 144);
;         p0 = __builtin_amdgcn_mfma_f32_32x32x16_bf16(a0, qr[0], MODE == MODE_SB ? z : negm, 0, 0, 0);
;         p1 = __builtin_amdgcn_mfma_f32_32x32x16_bf16(a1, qr[0], MODE == MODE_SB ? z : negm, 0, 0, 0); }
; #pragma unroll
;     for (int d0 = 1; d0 < 4; ++d0) {
;         const bf16x8 a0 = lds16(kp + d0 * 32), a1 = lds16(kp + 32 * 144 + d0 * 32);
;         p0 = __builtin_amdgcn_mfma_f32_32x32x16_bf16(a0, qr[d0], p0, 0, 0, 0);
;         p1 = __builtin_amdgcn_mfma_f32_32x32x16_bf16(a1, qr[d0], p1, 0, 0, 0);
;     }
;     ...
;     if (MODE == MODE_DIFF) {
;         if (k0 + 63 + 113 > qw0) {
;             LAS const float* rt = dtab + (207 - (qw0 - k0 + r32 - 4 * hi));
; #pragma unroll
;             for (int r = 0; r < 16; ++r) { p0[r] += rt[(r & 3) + 8 * (r >> 2)]; p1[r] += rt[(r & 3) + 8 * (r >> 2) + 32]; }
;         }
.LBB0_198:
	ds_read_b128 v[4:7], v222
	ds_read_b128 v[8:11], v222 offset:32
	s_sub_i32 s3, s51, 64
	s_cmp_le_u32 s3, s46
	s_waitcnt lgkmcnt(1)
	v_mfma_f32_32x32x16_bf16 v[112:127], v[4:7], v[136:139], v[80:95]
	ds_read_b128 v[4:7], v222 offset:4608
	ds_read_b128 v[12:15], v222 offset:4640
	s_waitcnt lgkmcnt(1)
	v_mfma_f32_32x32x16_bf16 v[96:111], v[4:7], v[136:139], v[80:95]
	v_mfma_f32_32x32x16_bf16 v[112:127], v[8:11], v[144:147], v[112:127]
	ds_read_b128 v[4:7], v222 offset:64
	ds_read_b128 v[8:11], v222 offset:96
	s_waitcnt lgkmcnt(2)
	v_mfma_f32_32x32x16_bf16 v[96:111], v[12:15], v[144:147], v[96:111]
	s_waitcnt lgkmcnt(1)
	v_mfma_f32_32x32x16_bf16 v[112:127], v[4:7], v[148:151], v[112:127]
	ds_read_b128 v[4:7], v222 offset:4672
	ds_read_b128 v[12:15], v222 offset:4704
	s_waitcnt lgkmcnt(1)
	v_mfma_f32_32x32x16_bf16 v[96:111], v[4:7], v[148:151], v[96:111]
	v_mfma_f32_32x32x16_bf16 v[112:127], v[8:11], v[152:155], v[112:127]
	s_waitcnt lgkmcnt(0)
	v_mfma_f32_32x32x16_bf16 v[96:111], v[12:15], v[152:155], v[96:111]
	s_cbranch_scc1 .LBB0_200
	v_add_u32_e32 v198, s47, v221
	v_add_u32_e32 v198, 0x2233c, v198
	ds_read2_b32 v[0:1], v198 offset1:1
	ds_read2_b32 v[4:5], v198 offset0:32 offset1:33
	ds_read2_b32 v[6:7], v198 offset0:2 offset1:3
	ds_read2_b32 v[8:9], v198 offset0:34 offset1:35
	ds_read2_b32 v[10:11], v198 offset0:8 offset1:9
	ds_read2_b32 v[12:13], v198 offset0:40 offset1:41
	ds_read2_b32 v[14:15], v198 offset0:10 offset1:11
	ds_read2_b32 v[194:195], v198 offset0:42 offset1:43
	ds_read2_b32 v[202:203], v198 offset0:16 offset1:17
	ds_read2_b32 v[222:223], v198 offset0:48 offset1:49
	ds_read2_b32 v[224:225], v198 offset0:18 offset1:19
	ds_read2_b32 v[226:227], v198 offset0:50 offset1:51
	ds_read2_b32 v[228:229], v198 offset0:26 offset1:27
	ds_read2_b32 v[230:231], v198 offset0:24 offset1:25
	ds_read2_b32 v[232:233], v198 offset0:56 offset1:57
	ds_read2_b32 v[234:235], v198 offset0:58 offset1:59
	s_waitcnt lgkmcnt(5)
	v_add_f32_e32 v122, v122, v224
	v_add_f32_e32 v123, v123, v225
	s_waitcnt lgkmcnt(3)
	v_add_f32_e32 v126, v126, v228
	v_add_f32_e32 v127, v127, v229
	s_waitcnt lgkmcnt(2)
	v_add_f32_e32 v124, v124, v230
	v_add_f32_e32 v125, v125, v231
	v_add_f32_e32 v120, v120, v202
	v_add_f32_e32 v121, v121, v203
	v_add_f32_e32 v118, v118, v14
	v_add_f32_e32 v119, v119, v15
	v_add_f32_e32 v116, v116, v10
	v_add_f32_e32 v117, v117, v11
	v_add_f32_e32 v114, v114, v6
	v_add_f32_e32 v115, v115, v7
	v_add_f32_e32 v112, v112, v0
	v_add_f32_e32 v113, v113, v1
	s_waitcnt lgkmcnt(0)
	v_add_f32_e32 v110, v110, v234
	v_add_f32_e32 v111, v111, v235
	v_add_f32_e32 v108, v108, v232
	v_add_f32_e32 v109, v109, v233
	v_add_f32_e32 v106, v106, v226
	v_add_f32_e32 v107, v107, v227
	v_add_f32_e32 v104, v104, v222
	v_add_f32_e32 v105, v105, v223
	v_add_f32_e32 v102, v102, v194
	v_add_f32_e32 v103, v103, v195
	v_add_f32_e32 v100, v100, v12
	v_add_f32_e32 v101, v101, v13
	v_add_f32_e32 v98, v98, v8
	v_add_f32_e32 v99, v99, v9
	v_add_f32_e32 v96, v96, v4
	v_add_f32_e32 v97, v97, v5
